# skip the redundant cooperative-groups grid.sync handshake at kernel entry (xcd barrier has its own census)
# speedup vs baseline: 1.0353x; 1.0117x over previous
; __global__ void __launch_bounds__(512, 2) mega_fwd(Args args) {
;     ...
;     if (threadIdx.x < 16) bst[threadIdx.x] = 0u;
;     __syncthreads();
;     XcdBarrier xbar = xcd_barrier_post((unsigned*)(args.ws), bst);
;     grid.sync();
.LBB0_5:
	s_or_b64 exec, exec, s[4:5]
	v_lshrrev_b32_e32 v1, 20, v0
	v_lshrrev_b32_e32 v0, 10, v0
	v_or_b32_e32 v0, v0, v1
	s_movk_i32 s1, 0x3ff
	v_and_or_b32 v0, v0, s1, v212
	v_cmp_eq_u32_e32 vcc, 0, v0
	s_barrier
	s_and_saveexec_b64 s[4:5], vcc
	s_branch .LBB0_15
